# lru_carry (blocks 0-3, tail of the prep phase): all 128 operand loads issued up front instead of 64 dependent round trips; same fmac chain
# speedup vs baseline: 1.0100x; 1.0100x over previous
.LBB0_877:
	s_mov_b32 s2, s87
	s_waitcnt vmcnt(0)
	v_mov_b32_e32 v0, v228
	s_nop 0
	v_lshl_add_u32 v1, s2, 9, v0
	s_movk_i32 s2, 0x800
	v_cmp_gt_i32_e32 vcc, s2, v1
	s_and_saveexec_b64 s[4:5], vcc
	s_mov_b64 s[12:13], 0x8000
	s_cbranch_execz .LBB0_880
	v_and_b32_e32 v2, 0x1ff, v1
	v_lshrrev_b32_e32 v3, 9, v1
	v_lshlrev_b32_e32 v3, 17, v3
	v_lshl_or_b32 v20, v2, 2, v3
	s_add_u32 s8, s44, 0x1d380000
	s_addc_u32 s9, s45, 0
	s_add_u32 s12, s44, 0x1d400000
	s_addc_u32 s13, s45, 0
	s_add_u32 s98, s44, 0x1d480000
	s_addc_u32 s99, s45, 0
	v_add_u32_e32 v21, 0x800, v20
	v_add_u32_e32 v22, 0x1000, v20
	v_add_u32_e32 v23, 0x1800, v20
	v_add_u32_e32 v24, 0x2000, v20
	v_add_u32_e32 v25, 0x2800, v20
	v_add_u32_e32 v26, 0x3000, v20
	v_add_u32_e32 v27, 0x3800, v20
	v_add_u32_e32 v28, 0x4000, v20
	v_add_u32_e32 v29, 0x4800, v20
	v_add_u32_e32 v30, 0x5000, v20
	v_add_u32_e32 v31, 0x5800, v20
	v_add_u32_e32 v32, 0x6000, v20
	v_add_u32_e32 v33, 0x6800, v20
	v_add_u32_e32 v34, 0x7000, v20
	v_add_u32_e32 v35, 0x7800, v20
	v_add_u32_e32 v36, 0x8000, v20
	v_add_u32_e32 v37, 0x8800, v20
	v_add_u32_e32 v38, 0x9000, v20
	v_add_u32_e32 v39, 0x9800, v20
	v_add_u32_e32 v40, 0xa000, v20
	v_add_u32_e32 v41, 0xa800, v20
	v_add_u32_e32 v42, 0xb000, v20
	v_add_u32_e32 v43, 0xb800, v20
	v_add_u32_e32 v44, 0xc000, v20
	v_add_u32_e32 v45, 0xc800, v20
	v_add_u32_e32 v46, 0xd000, v20
	v_add_u32_e32 v47, 0xd800, v20
	v_add_u32_e32 v48, 0xe000, v20
	v_add_u32_e32 v49, 0xe800, v20
	v_add_u32_e32 v50, 0xf000, v20
	v_add_u32_e32 v51, 0xf800, v20
	v_add_u32_e32 v52, 0x10000, v20
	v_add_u32_e32 v53, 0x10800, v20
	v_add_u32_e32 v54, 0x11000, v20
	v_add_u32_e32 v55, 0x11800, v20
	v_add_u32_e32 v56, 0x12000, v20
	v_add_u32_e32 v57, 0x12800, v20
	v_add_u32_e32 v58, 0x13000, v20
	v_add_u32_e32 v59, 0x13800, v20
	v_add_u32_e32 v60, 0x14000, v20
	v_add_u32_e32 v61, 0x14800, v20
	v_add_u32_e32 v62, 0x15000, v20
	v_add_u32_e32 v63, 0x15800, v20
	v_add_u32_e32 v64, 0x16000, v20
	v_add_u32_e32 v65, 0x16800, v20
	v_add_u32_e32 v66, 0x17000, v20
	v_add_u32_e32 v67, 0x17800, v20
	v_add_u32_e32 v68, 0x18000, v20
	v_add_u32_e32 v69, 0x18800, v20
	v_add_u32_e32 v70, 0x19000, v20
	v_add_u32_e32 v71, 0x19800, v20
	v_add_u32_e32 v72, 0x1a000, v20
	v_add_u32_e32 v73, 0x1a800, v20
	v_add_u32_e32 v74, 0x1b000, v20
	v_add_u32_e32 v75, 0x1b800, v20
	v_add_u32_e32 v76, 0x1c000, v20
	v_add_u32_e32 v77, 0x1c800, v20
	v_add_u32_e32 v78, 0x1d000, v20
	v_add_u32_e32 v79, 0x1d800, v20
	v_add_u32_e32 v80, 0x1e000, v20
	v_add_u32_e32 v81, 0x1e800, v20
	v_add_u32_e32 v82, 0x1f000, v20
	v_add_u32_e32 v83, 0x1f800, v20
	global_load_dword v84, v20, s[8:9]
	global_load_dword v148, v20, s[12:13]
	global_load_dword v85, v21, s[8:9]
	global_load_dword v149, v21, s[12:13]
	global_load_dword v86, v22, s[8:9]
	global_load_dword v150, v22, s[12:13]
	global_load_dword v87, v23, s[8:9]
	global_load_dword v151, v23, s[12:13]
	global_load_dword v88, v24, s[8:9]
	global_load_dword v152, v24, s[12:13]
	global_load_dword v89, v25, s[8:9]
	global_load_dword v153, v25, s[12:13]
	global_load_dword v90, v26, s[8:9]
	global_load_dword v154, v26, s[12:13]
	global_load_dword v91, v27, s[8:9]
	global_load_dword v155, v27, s[12:13]
	global_load_dword v92, v28, s[8:9]
	global_load_dword v156, v28, s[12:13]
	global_load_dword v93, v29, s[8:9]
	global_load_dword v157, v29, s[12:13]
	global_load_dword v94, v30, s[8:9]
	global_load_dword v158, v30, s[12:13]
	global_load_dword v95, v31, s[8:9]
	global_load_dword v159, v31, s[12:13]
	global_load_dword v96, v32, s[8:9]
	global_load_dword v160, v32, s[12:13]
	global_load_dword v97, v33, s[8:9]
	global_load_dword v161, v33, s[12:13]
	global_load_dword v98, v34, s[8:9]
	global_load_dword v162, v34, s[12:13]
	global_load_dword v99, v35, s[8:9]
	global_load_dword v163, v35, s[12:13]
	global_load_dword v100, v36, s[8:9]
	global_load_dword v164, v36, s[12:13]
	global_load_dword v101, v37, s[8:9]
	global_load_dword v165, v37, s[12:13]
	global_load_dword v102, v38, s[8:9]
	global_load_dword v166, v38, s[12:13]
	global_load_dword v103, v39, s[8:9]
	global_load_dword v167, v39, s[12:13]
	global_load_dword v104, v40, s[8:9]
	global_load_dword v168, v40, s[12:13]
	global_load_dword v105, v41, s[8:9]
	global_load_dword v169, v41, s[12:13]
	global_load_dword v106, v42, s[8:9]
	global_load_dword v170, v42, s[12:13]
	global_load_dword v107, v43, s[8:9]
	global_load_dword v171, v43, s[12:13]
	global_load_dword v108, v44, s[8:9]
	global_load_dword v172, v44, s[12:13]
	global_load_dword v109, v45, s[8:9]
	global_load_dword v173, v45, s[12:13]
	global_load_dword v110, v46, s[8:9]
	global_load_dword v174, v46, s[12:13]
	global_load_dword v111, v47, s[8:9]
	global_load_dword v175, v47, s[12:13]
	global_load_dword v112, v48, s[8:9]
	global_load_dword v176, v48, s[12:13]
	global_load_dword v113, v49, s[8:9]
	global_load_dword v177, v49, s[12:13]
	global_load_dword v114, v50, s[8:9]
	global_load_dword v178, v50, s[12:13]
	global_load_dword v115, v51, s[8:9]
	global_load_dword v179, v51, s[12:13]
	global_load_dword v116, v52, s[8:9]
	global_load_dword v180, v52, s[12:13]
	global_load_dword v117, v53, s[8:9]
	global_load_dword v181, v53, s[12:13]
	global_load_dword v118, v54, s[8:9]
	global_load_dword v182, v54, s[12:13]
	global_load_dword v119, v55, s[8:9]
	global_load_dword v183, v55, s[12:13]
	global_load_dword v120, v56, s[8:9]
	global_load_dword v184, v56, s[12:13]
	global_load_dword v121, v57, s[8:9]
	global_load_dword v185, v57, s[12:13]
	global_load_dword v122, v58, s[8:9]
	global_load_dword v186, v58, s[12:13]
	global_load_dword v123, v59, s[8:9]
	global_load_dword v187, v59, s[12:13]
	global_load_dword v124, v60, s[8:9]
	global_load_dword v188, v60, s[12:13]
	global_load_dword v125, v61, s[8:9]
	global_load_dword v189, v61, s[12:13]
	global_load_dword v126, v62, s[8:9]
	global_load_dword v190, v62, s[12:13]
	global_load_dword v127, v63, s[8:9]
	global_load_dword v191, v63, s[12:13]
	global_load_dword v128, v64, s[8:9]
	global_load_dword v192, v64, s[12:13]
	global_load_dword v129, v65, s[8:9]
	global_load_dword v193, v65, s[12:13]
	global_load_dword v130, v66, s[8:9]
	global_load_dword v194, v66, s[12:13]
	global_load_dword v131, v67, s[8:9]
	global_load_dword v195, v67, s[12:13]
	global_load_dword v132, v68, s[8:9]
	global_load_dword v196, v68, s[12:13]
	global_load_dword v133, v69, s[8:9]
	global_load_dword v197, v69, s[12:13]
	global_load_dword v134, v70, s[8:9]
	global_load_dword v208, v70, s[12:13]
	global_load_dword v135, v71, s[8:9]
	global_load_dword v209, v71, s[12:13]
	global_load_dword v136, v72, s[8:9]
	global_load_dword v210, v72, s[12:13]
	global_load_dword v137, v73, s[8:9]
	global_load_dword v211, v73, s[12:13]
	global_load_dword v138, v74, s[8:9]
	global_load_dword v212, v74, s[12:13]
	global_load_dword v139, v75, s[8:9]
	global_load_dword v213, v75, s[12:13]
	global_load_dword v140, v76, s[8:9]
	global_load_dword v214, v76, s[12:13]
	global_load_dword v141, v77, s[8:9]
	global_load_dword v215, v77, s[12:13]
	global_load_dword v142, v78, s[8:9]
	global_load_dword v216, v78, s[12:13]
	global_load_dword v143, v79, s[8:9]
	global_load_dword v217, v79, s[12:13]
	global_load_dword v144, v80, s[8:9]
	global_load_dword v218, v80, s[12:13]
	global_load_dword v145, v81, s[8:9]
	global_load_dword v219, v81, s[12:13]
	global_load_dword v146, v82, s[8:9]
	global_load_dword v220, v82, s[12:13]
	global_load_dword v147, v83, s[8:9]
	global_load_dword v221, v83, s[12:13]
	s_waitcnt vmcnt(0)
	global_store_dword v20, v17, s[98:99]
	v_fmac_f32_e32 v148, v17, v84
	global_store_dword v21, v148, s[98:99]
	v_fmac_f32_e32 v149, v148, v85
	global_store_dword v22, v149, s[98:99]
	v_fmac_f32_e32 v150, v149, v86
	global_store_dword v23, v150, s[98:99]
	v_fmac_f32_e32 v151, v150, v87
	global_store_dword v24, v151, s[98:99]
	v_fmac_f32_e32 v152, v151, v88
	global_store_dword v25, v152, s[98:99]
	v_fmac_f32_e32 v153, v152, v89
	global_store_dword v26, v153, s[98:99]
	v_fmac_f32_e32 v154, v153, v90
	global_store_dword v27, v154, s[98:99]
	v_fmac_f32_e32 v155, v154, v91
	global_store_dword v28, v155, s[98:99]
	v_fmac_f32_e32 v156, v155, v92
	global_store_dword v29, v156, s[98:99]
	v_fmac_f32_e32 v157, v156, v93
	global_store_dword v30, v157, s[98:99]
	v_fmac_f32_e32 v158, v157, v94
	global_store_dword v31, v158, s[98:99]
	v_fmac_f32_e32 v159, v158, v95
	global_store_dword v32, v159, s[98:99]
	v_fmac_f32_e32 v160, v159, v96
	global_store_dword v33, v160, s[98:99]
	v_fmac_f32_e32 v161, v160, v97
	global_store_dword v34, v161, s[98:99]
	v_fmac_f32_e32 v162, v161, v98
	global_store_dword v35, v162, s[98:99]
	v_fmac_f32_e32 v163, v162, v99
	global_store_dword v36, v163, s[98:99]
	v_fmac_f32_e32 v164, v163, v100
	global_store_dword v37, v164, s[98:99]
	v_fmac_f32_e32 v165, v164, v101
	global_store_dword v38, v165, s[98:99]
	v_fmac_f32_e32 v166, v165, v102
	global_store_dword v39, v166, s[98:99]
	v_fmac_f32_e32 v167, v166, v103
	global_store_dword v40, v167, s[98:99]
	v_fmac_f32_e32 v168, v167, v104
	global_store_dword v41, v168, s[98:99]
	v_fmac_f32_e32 v169, v168, v105
	global_store_dword v42, v169, s[98:99]
	v_fmac_f32_e32 v170, v169, v106
	global_store_dword v43, v170, s[98:99]
	v_fmac_f32_e32 v171, v170, v107
	global_store_dword v44, v171, s[98:99]
	v_fmac_f32_e32 v172, v171, v108
	global_store_dword v45, v172, s[98:99]
	v_fmac_f32_e32 v173, v172, v109
	global_store_dword v46, v173, s[98:99]
	v_fmac_f32_e32 v174, v173, v110
	global_store_dword v47, v174, s[98:99]
	v_fmac_f32_e32 v175, v174, v111
	global_store_dword v48, v175, s[98:99]
	v_fmac_f32_e32 v176, v175, v112
	global_store_dword v49, v176, s[98:99]
	v_fmac_f32_e32 v177, v176, v113
	global_store_dword v50, v177, s[98:99]
	v_fmac_f32_e32 v178, v177, v114
	global_store_dword v51, v178, s[98:99]
	v_fmac_f32_e32 v179, v178, v115
	global_store_dword v52, v179, s[98:99]
	v_fmac_f32_e32 v180, v179, v116
	global_store_dword v53, v180, s[98:99]
	v_fmac_f32_e32 v181, v180, v117
	global_store_dword v54, v181, s[98:99]
	v_fmac_f32_e32 v182, v181, v118
	global_store_dword v55, v182, s[98:99]
	v_fmac_f32_e32 v183, v182, v119
	global_store_dword v56, v183, s[98:99]
	v_fmac_f32_e32 v184, v183, v120
	global_store_dword v57, v184, s[98:99]
	v_fmac_f32_e32 v185, v184, v121
	global_store_dword v58, v185, s[98:99]
	v_fmac_f32_e32 v186, v185, v122
	global_store_dword v59, v186, s[98:99]
	v_fmac_f32_e32 v187, v186, v123
	global_store_dword v60, v187, s[98:99]
	v_fmac_f32_e32 v188, v187, v124
	global_store_dword v61, v188, s[98:99]
	v_fmac_f32_e32 v189, v188, v125
	global_store_dword v62, v189, s[98:99]
	v_fmac_f32_e32 v190, v189, v126
	global_store_dword v63, v190, s[98:99]
	v_fmac_f32_e32 v191, v190, v127
	global_store_dword v64, v191, s[98:99]
	v_fmac_f32_e32 v192, v191, v128
	global_store_dword v65, v192, s[98:99]
	v_fmac_f32_e32 v193, v192, v129
	global_store_dword v66, v193, s[98:99]
	v_fmac_f32_e32 v194, v193, v130
	global_store_dword v67, v194, s[98:99]
	v_fmac_f32_e32 v195, v194, v131
	global_store_dword v68, v195, s[98:99]
	v_fmac_f32_e32 v196, v195, v132
	global_store_dword v69, v196, s[98:99]
	v_fmac_f32_e32 v197, v196, v133
	global_store_dword v70, v197, s[98:99]
	v_fmac_f32_e32 v208, v197, v134
	global_store_dword v71, v208, s[98:99]
	v_fmac_f32_e32 v209, v208, v135
	global_store_dword v72, v209, s[98:99]
	v_fmac_f32_e32 v210, v209, v136
	global_store_dword v73, v210, s[98:99]
	v_fmac_f32_e32 v211, v210, v137
	global_store_dword v74, v211, s[98:99]
	v_fmac_f32_e32 v212, v211, v138
	global_store_dword v75, v212, s[98:99]
	v_fmac_f32_e32 v213, v212, v139
	global_store_dword v76, v213, s[98:99]
	v_fmac_f32_e32 v214, v213, v140
	global_store_dword v77, v214, s[98:99]
	v_fmac_f32_e32 v215, v214, v141
	global_store_dword v78, v215, s[98:99]
	v_fmac_f32_e32 v216, v215, v142
	global_store_dword v79, v216, s[98:99]
	v_fmac_f32_e32 v217, v216, v143
	global_store_dword v80, v217, s[98:99]
	v_fmac_f32_e32 v218, v217, v144
	global_store_dword v81, v218, s[98:99]
	v_fmac_f32_e32 v219, v218, v145
	global_store_dword v82, v219, s[98:99]
	v_fmac_f32_e32 v220, v219, v146
	global_store_dword v83, v220, s[98:99]
	v_fmac_f32_e32 v221, v220, v147
